# v114 + in-proj K-loop: the LDS-DMA stage loads are issued first in every load segment (before the fragment ds_reads) with SGPR-base addressing (no 64-bit VALU address adds)
# speedup vs baseline: 1.0033x; 1.0033x over previous
; #define PG8_STAGE(bufoff, gbase, voff) do { _Pragma("unroll") for (int _i = 0; _i < 2; ++_i) \
;         __builtin_amdgcn_global_load_lds((const unsigned*)((const char*)(gbase) + (voff)[_i]), (PG8_LAS unsigned*)(lds + (bufoff) + ldsw + _i * 8192), 16, 0, 0); } while (0)
; #define PG8_LDA(dst, b, h) do { _Pragma("unroll") for (int m = 0; m < 4; ++m) _Pragma("unroll") for (int k = 0; k < 2; ++k) dst[m][k] = *(const PG8_LAS bf16x8*)(lds + PG8_SA(b, h) + aoff + m * 2048 + k * 1024); } while (0)
; #define PG8_LDB(dst, b, h) do { _Pragma("unroll") for (int n = 0; n < 2; ++n) _Pragma("unroll") for (int k = 0; k < 2; ++k) dst[n][k] = *(const PG8_LAS bf16x8*)(lds + PG8_SB(b, h) + boff + n * 2048 + k * 1024); } while (0)
; #define PG8_MMA(ai, bj, At, Bt) do { __builtin_amdgcn_s_setprio(1); _Pragma("unroll") for (int m = 0; m < 4; ++m) _Pragma("unroll") for (int n = 0; n < 2; ++n) _Pragma("unroll") for (int k = 0; k < 2; ++k) \
;         acc[ai][bj][m][n] = __builtin_amdgcn_mfma_f32_16x16x32_bf16(Bt[n][k], At[m][k], acc[ai][bj][m][n], 0, 0, 0); __builtin_amdgcn_s_setprio(0); } while (0)
; #define PG8_WAIT_V(n) asm volatile("s_waitcnt vmcnt(" #n ")" ::: "memory")
; #define PG8_WAIT_L(n) asm volatile("s_waitcnt lgkmcnt(" #n ")" ::: "memory")
; #define PG8_BAR __builtin_amdgcn_s_barrier()
; #define PG8_SCHED __builtin_amdgcn_sched_barrier(0)
; template <class Epi, class Sched, bool ALIGN_EPI = false, bool SP2 = false>
; __device__ __forceinline__ void gemm_phase(PG8_LAS unsigned char* lds, const Gemm g, const Sched& S, const Epi& E) {
;     ...
;             PG8_LDB(B0, 0, 0); PG8_LDB(B1, 0, 1); PG8_SCHED; PG8_LDA(At, 0, 0); PG8_STAGE(PG8_SA(1, 1), a1 + hstep, voffA);
;             PG8_WAIT_V(8); PG8_WAIT_L(0); PG8_BAR; PG8_MMA(0, 0, At, B0); PG8_MMA(0, 1, At, B1); PG8_BAR; PG8_SCHED;
;             PG8_LDA(At, 0, 1); PG8_STAGE(PG8_SB(0, 0), b2, voffB); PG8_STAGE(PG8_SB(0, 1), b2 + hstep, voffB); PG8_STAGE(PG8_SA(0, 0), a2, voffA);
;             PG8_WAIT_V(8); PG8_WAIT_L(0); PG8_BAR; PG8_MMA(1, 0, At, B0); PG8_MMA(1, 1, At, B1); PG8_BAR; PG8_SCHED;
.LBB0_274:
	s_add_i32 m0, s19, 0xc000
	s_nop 0
	global_load_lds_dwordx4 v136, s[20:21]
	s_add_i32 m0, s19, 0xe000
	s_nop 0
	global_load_lds_dwordx4 v138, s[20:21]
	s_add_u32 s22, s20, 0xfffc0080
	s_addc_u32 s23, s21, -1
	s_add_i32 s39, 0, 0x10000
	s_cmp_eq_u32 s38, 12
	s_cselect_b32 s25, s5, s23
	s_cselect_b32 s24, s13, s22
	v_add_u32_e32 v148, s39, v151
	s_cselect_b32 s23, s11, s37
	s_cselect_b32 s22, s35, s36
	s_add_i32 s45, 0, 0x14000
	ds_read_b128 v[140:143], v148
	ds_read_b128 v[144:147], v148 offset:1024
	ds_read_b128 v[156:159], v148 offset:2048
	ds_read_b128 v[160:163], v148 offset:3072
	v_add_u32_e32 v148, s45, v151
	ds_read_b128 v[164:167], v148
	ds_read_b128 v[168:171], v148 offset:1024
	ds_read_b128 v[182:185], v148 offset:2048
	ds_read_b128 v[186:189], v148 offset:3072
	ds_read_b128 v[190:193], v154
	ds_read_b128 v[194:197], v154 offset:1024
	ds_read_b128 v[198:201], v154 offset:2048
	ds_read_b128 v[202:205], v154 offset:3072
	ds_read_b128 v[228:231], v154 offset:4096
	ds_read_b128 v[236:239], v154 offset:5120
	ds_read_b128 v[240:243], v154 offset:6144
	ds_read_b128 v[244:247], v154 offset:7168
	s_waitcnt vmcnt(8)
	s_waitcnt lgkmcnt(0)
	s_barrier
	s_setprio 1
	s_waitcnt lgkmcnt(0)
	v_mfma_f32_16x16x32_bf16 v[124:127], v[140:143], v[190:193], v[124:127]
	v_mfma_f32_16x16x32_bf16 v[120:123], v[156:159], v[190:193], v[120:123]
	v_mfma_f32_16x16x32_bf16 v[108:111], v[140:143], v[198:201], v[108:111]
	v_mfma_f32_16x16x32_bf16 v[104:107], v[156:159], v[198:201], v[104:107]
	v_mfma_f32_16x16x32_bf16 v[92:95], v[140:143], v[228:231], v[92:95]
	v_mfma_f32_16x16x32_bf16 v[88:91], v[156:159], v[228:231], v[88:91]
	v_mfma_f32_16x16x32_bf16 v[76:79], v[140:143], v[240:243], v[76:79]
	v_mfma_f32_16x16x32_bf16 v[72:75], v[156:159], v[240:243], v[72:75]
	v_mfma_f32_16x16x32_bf16 v[124:127], v[144:147], v[194:197], v[124:127]
	v_mfma_f32_16x16x32_bf16 v[120:123], v[160:163], v[194:197], v[120:123]
	v_mfma_f32_16x16x32_bf16 v[108:111], v[144:147], v[202:205], v[108:111]
	v_mfma_f32_16x16x32_bf16 v[104:107], v[160:163], v[202:205], v[104:107]
	v_mfma_f32_16x16x32_bf16 v[92:95], v[144:147], v[236:239], v[92:95]
	v_mfma_f32_16x16x32_bf16 v[88:91], v[160:163], v[236:239], v[88:91]
	v_mfma_f32_16x16x32_bf16 v[76:79], v[144:147], v[244:247], v[76:79]
	v_mfma_f32_16x16x32_bf16 v[72:75], v[160:163], v[244:247], v[72:75]
	s_setprio 0
	s_setprio 1
	v_mfma_f32_16x16x32_bf16 v[116:119], v[164:167], v[190:193], v[116:119]
	v_mfma_f32_16x16x32_bf16 v[112:115], v[182:185], v[190:193], v[112:115]
	v_mfma_f32_16x16x32_bf16 v[100:103], v[164:167], v[198:201], v[100:103]
	v_mfma_f32_16x16x32_bf16 v[96:99], v[182:185], v[198:201], v[96:99]
	v_mfma_f32_16x16x32_bf16 v[84:87], v[164:167], v[228:231], v[84:87]
	v_mfma_f32_16x16x32_bf16 v[80:83], v[182:185], v[228:231], v[80:83]
	v_mfma_f32_16x16x32_bf16 v[68:71], v[164:167], v[240:243], v[68:71]
	v_mfma_f32_16x16x32_bf16 v[64:67], v[182:185], v[240:243], v[64:67]
	v_mfma_f32_16x16x32_bf16 v[116:119], v[168:171], v[194:197], v[116:119]
	v_mfma_f32_16x16x32_bf16 v[112:115], v[186:189], v[194:197], v[112:115]
	v_mfma_f32_16x16x32_bf16 v[100:103], v[168:171], v[202:205], v[100:103]
	v_mfma_f32_16x16x32_bf16 v[96:99], v[186:189], v[202:205], v[96:99]
	s_setprio 2
	s_barrier
	v_mfma_f32_16x16x32_bf16 v[84:87], v[168:171], v[236:239], v[84:87]
	v_mfma_f32_16x16x32_bf16 v[80:83], v[186:189], v[236:239], v[80:83]
	v_mfma_f32_16x16x32_bf16 v[68:71], v[168:171], v[244:247], v[68:71]
	v_mfma_f32_16x16x32_bf16 v[64:67], v[186:189], v[244:247], v[64:67]
	s_setprio 0
	s_add_i32 s39, s39, s26
	s_add_u32 s64, s22, 0x80
	s_addc_u32 s65, s23, 0
	s_add_u32 s68, s24, 0x80
	s_addc_u32 s69, s25, 0
	s_add_u32 s52, s22, 0x40000
	s_addc_u32 s53, s23, 0
	s_mov_b32 m0, s39
	s_nop 0
	global_load_lds_dwordx4 v130, s[22:23]
	s_add_i32 m0, s39, 0x2000
	s_nop 0
	global_load_lds_dwordx4 v134, s[22:23]
	s_add_i32 s39, s45, s26
	s_mov_b32 m0, s39
	s_nop 0
	global_load_lds_dwordx4 v130, s[52:53]
	s_add_i32 m0, s39, 0x2000
	s_nop 0
	global_load_lds_dwordx4 v134, s[52:53]
	s_mov_b32 m0, s19
	s_nop 0
	global_load_lds_dwordx4 v128, s[24:25]
	s_mov_b32 m0, s27
	s_nop 0
	global_load_lds_dwordx4 v132, s[24:25]
	ds_read_b128 v[190:193], v154 offset:16384
	ds_read_b128 v[194:197], v154 offset:17408
	ds_read_b128 v[198:201], v154 offset:18432
	ds_read_b128 v[202:205], v154 offset:19456
	ds_read_b128 v[228:231], v154 offset:20480
	ds_read_b128 v[236:239], v154 offset:21504
	ds_read_b128 v[240:243], v154 offset:22528
	ds_read_b128 v[244:247], v154 offset:23552
	s_waitcnt vmcnt(8)
	s_waitcnt lgkmcnt(0)
	s_barrier
	s_setprio 1
	s_waitcnt lgkmcnt(0)
	v_mfma_f32_16x16x32_bf16 v[60:63], v[140:143], v[190:193], v[60:63]
	v_mfma_f32_16x16x32_bf16 v[56:59], v[156:159], v[190:193], v[56:59]
	v_mfma_f32_16x16x32_bf16 v[44:47], v[140:143], v[198:201], v[44:47]
	v_mfma_f32_16x16x32_bf16 v[40:43], v[156:159], v[198:201], v[40:43]
	v_mfma_f32_16x16x32_bf16 v[28:31], v[140:143], v[228:231], v[28:31]
	v_mfma_f32_16x16x32_bf16 v[24:27], v[156:159], v[228:231], v[24:27]
	v_mfma_f32_16x16x32_bf16 v[12:15], v[140:143], v[240:243], v[12:15]
	v_mfma_f32_16x16x32_bf16 v[8:11], v[156:159], v[240:243], v[8:11]
	v_mfma_f32_16x16x32_bf16 v[60:63], v[144:147], v[194:197], v[60:63]
	v_mfma_f32_16x16x32_bf16 v[56:59], v[160:163], v[194:197], v[56:59]
	v_mfma_f32_16x16x32_bf16 v[44:47], v[144:147], v[202:205], v[44:47]
	v_mfma_f32_16x16x32_bf16 v[40:43], v[160:163], v[202:205], v[40:43]
	v_mfma_f32_16x16x32_bf16 v[28:31], v[144:147], v[236:239], v[28:31]
	v_mfma_f32_16x16x32_bf16 v[24:27], v[160:163], v[236:239], v[24:27]
	v_mfma_f32_16x16x32_bf16 v[12:15], v[144:147], v[244:247], v[12:15]
	v_mfma_f32_16x16x32_bf16 v[8:11], v[160:163], v[244:247], v[8:11]
	s_setprio 0
	s_setprio 1
	v_mfma_f32_16x16x32_bf16 v[52:55], v[164:167], v[190:193], v[52:55]
	v_mfma_f32_16x16x32_bf16 v[48:51], v[182:185], v[190:193], v[48:51]
	v_mfma_f32_16x16x32_bf16 v[36:39], v[164:167], v[198:201], v[36:39]
	v_mfma_f32_16x16x32_bf16 v[32:35], v[182:185], v[198:201], v[32:35]
	v_mfma_f32_16x16x32_bf16 v[20:23], v[164:167], v[228:231], v[20:23]
	v_mfma_f32_16x16x32_bf16 v[16:19], v[182:185], v[228:231], v[16:19]
	v_mfma_f32_16x16x32_bf16 v[4:7], v[164:167], v[240:243], v[4:7]
	v_mfma_f32_16x16x32_bf16 v[0:3], v[182:185], v[240:243], v[0:3]
	v_mfma_f32_16x16x32_bf16 v[52:55], v[168:171], v[194:197], v[52:55]
	v_mfma_f32_16x16x32_bf16 v[48:51], v[186:189], v[194:197], v[48:51]
	v_mfma_f32_16x16x32_bf16 v[36:39], v[168:171], v[202:205], v[36:39]
	v_mfma_f32_16x16x32_bf16 v[32:35], v[186:189], v[202:205], v[32:35]
	s_setprio 2
	s_barrier
; #define PG8_STAGE(bufoff, gbase, voff) do { _Pragma("unroll") for (int _i = 0; _i < 2; ++_i) \
;         __builtin_amdgcn_global_load_lds((const unsigned*)((const char*)(gbase) + (voff)[_i]), (PG8_LAS unsigned*)(lds + (bufoff) + ldsw + _i * 8192), 16, 0, 0); } while (0)
; #define PG8_LDA(dst, b, h) do { _Pragma("unroll") for (int m = 0; m < 4; ++m) _Pragma("unroll") for (int k = 0; k < 2; ++k) dst[m][k] = *(const PG8_LAS bf16x8*)(lds + PG8_SA(b, h) + aoff + m * 2048 + k * 1024); } while (0)
; #define PG8_LDB(dst, b, h) do { _Pragma("unroll") for (int n = 0; n < 2; ++n) _Pragma("unroll") for (int k = 0; k < 2; ++k) dst[n][k] = *(const PG8_LAS bf16x8*)(lds + PG8_SB(b, h) + boff + n * 2048 + k * 1024); } while (0)
; #define PG8_MMA(ai, bj, At, Bt) do { __builtin_amdgcn_s_setprio(1); _Pragma("unroll") for (int m = 0; m < 4; ++m) _Pragma("unroll") for (int n = 0; n < 2; ++n) _Pragma("unroll") for (int k = 0; k < 2; ++k) \
;         acc[ai][bj][m][n] = __builtin_amdgcn_mfma_f32_16x16x32_bf16(Bt[n][k], At[m][k], acc[ai][bj][m][n], 0, 0, 0); __builtin_amdgcn_s_setprio(0); } while (0)
; #define PG8_WAIT_V(n) asm volatile("s_waitcnt vmcnt(" #n ")" ::: "memory")
; #define PG8_WAIT_L(n) asm volatile("s_waitcnt lgkmcnt(" #n ")" ::: "memory")
; #define PG8_BAR __builtin_amdgcn_s_barrier()
; #define PG8_SCHED __builtin_amdgcn_sched_barrier(0)
; template <class Epi, class Sched, bool ALIGN_EPI = false, bool SP2 = false>
; __device__ __forceinline__ void gemm_phase(PG8_LAS unsigned char* lds, const Gemm g, const Sched& S, const Epi& E) {
;     ...
;             PG8_WAIT_V(8); PG8_WAIT_L(0); PG8_BAR; PG8_MMA(1, 0, At, B0); PG8_MMA(1, 1, At, B1); PG8_BAR; PG8_SCHED;
;             PG8_LDB(B0, 1, 0); PG8_LDB(B1, 1, 1); PG8_SCHED; PG8_LDA(At, 1, 0); PG8_STAGE(PG8_SA(0, 1), a2 + hstep, voffA);
;             PG8_WAIT_V(8); PG8_WAIT_L(0); PG8_BAR; PG8_MMA(0, 0, At, B0); PG8_MMA(0, 1, At, B1); PG8_BAR; PG8_SCHED;
	v_mfma_f32_16x16x32_bf16 v[20:23], v[168:171], v[236:239], v[20:23]
	v_mfma_f32_16x16x32_bf16 v[16:19], v[186:189], v[236:239], v[16:19]
	v_mfma_f32_16x16x32_bf16 v[4:7], v[168:171], v[244:247], v[4:7]
	v_mfma_f32_16x16x32_bf16 v[0:3], v[186:189], v[244:247], v[0:3]
	s_setprio 0
	s_add_u32 s24, s24, 0x40000
	s_addc_u32 s25, s25, 0
	s_mov_b32 m0, s28
	s_nop 0
	global_load_lds_dwordx4 v128, s[24:25]
	s_mov_b32 m0, s29
	s_nop 0
	global_load_lds_dwordx4 v132, s[24:25]
	s_add_i32 s39, 0, 0x18000
	v_add_u32_e32 v155, s39, v151
	s_add_i32 s45, 0, 0x1c000
	ds_read_b128 v[140:143], v155
	ds_read_b128 v[144:147], v155 offset:1024
	ds_read_b128 v[156:159], v155 offset:2048
	ds_read_b128 v[160:163], v155 offset:3072
	v_add_u32_e32 v155, s45, v151
	ds_read_b128 v[164:167], v155
	ds_read_b128 v[168:171], v155 offset:1024
	ds_read_b128 v[182:185], v155 offset:2048
	ds_read_b128 v[186:189], v155 offset:3072
	ds_read_b128 v[190:193], v154 offset:32768
	ds_read_b128 v[194:197], v154 offset:33792
	ds_read_b128 v[198:201], v154 offset:34816
	ds_read_b128 v[202:205], v154 offset:35840
	ds_read_b128 v[228:231], v154 offset:36864
	ds_read_b128 v[236:239], v154 offset:37888
	ds_read_b128 v[240:243], v154 offset:38912
	ds_read_b128 v[244:247], v154 offset:39936
	s_waitcnt vmcnt(8)
	s_waitcnt lgkmcnt(0)
	s_barrier
	s_setprio 1
	s_waitcnt lgkmcnt(0)
	v_mfma_f32_16x16x32_bf16 v[124:127], v[140:143], v[190:193], v[124:127]
	v_mfma_f32_16x16x32_bf16 v[120:123], v[156:159], v[190:193], v[120:123]
	v_mfma_f32_16x16x32_bf16 v[108:111], v[140:143], v[198:201], v[108:111]
	v_mfma_f32_16x16x32_bf16 v[104:107], v[156:159], v[198:201], v[104:107]
	v_mfma_f32_16x16x32_bf16 v[92:95], v[140:143], v[228:231], v[92:95]
	v_mfma_f32_16x16x32_bf16 v[88:91], v[156:159], v[228:231], v[88:91]
	v_mfma_f32_16x16x32_bf16 v[76:79], v[140:143], v[240:243], v[76:79]
	v_mfma_f32_16x16x32_bf16 v[72:75], v[156:159], v[240:243], v[72:75]
	v_mfma_f32_16x16x32_bf16 v[124:127], v[144:147], v[194:197], v[124:127]
	v_mfma_f32_16x16x32_bf16 v[120:123], v[160:163], v[194:197], v[120:123]
	v_mfma_f32_16x16x32_bf16 v[108:111], v[144:147], v[202:205], v[108:111]
	v_mfma_f32_16x16x32_bf16 v[104:107], v[160:163], v[202:205], v[104:107]
	v_mfma_f32_16x16x32_bf16 v[92:95], v[144:147], v[236:239], v[92:95]
	v_mfma_f32_16x16x32_bf16 v[88:91], v[160:163], v[236:239], v[88:91]
	v_mfma_f32_16x16x32_bf16 v[76:79], v[144:147], v[244:247], v[76:79]
	v_mfma_f32_16x16x32_bf16 v[72:75], v[160:163], v[244:247], v[72:75]
	s_setprio 0
	s_setprio 1
	v_mfma_f32_16x16x32_bf16 v[116:119], v[164:167], v[190:193], v[116:119]
	v_mfma_f32_16x16x32_bf16 v[112:115], v[182:185], v[190:193], v[112:115]
	v_mfma_f32_16x16x32_bf16 v[100:103], v[164:167], v[198:201], v[100:103]
	v_mfma_f32_16x16x32_bf16 v[96:99], v[182:185], v[198:201], v[96:99]
	v_mfma_f32_16x16x32_bf16 v[84:87], v[164:167], v[228:231], v[84:87]
	v_mfma_f32_16x16x32_bf16 v[80:83], v[182:185], v[228:231], v[80:83]
	v_mfma_f32_16x16x32_bf16 v[68:71], v[164:167], v[240:243], v[68:71]
	v_mfma_f32_16x16x32_bf16 v[64:67], v[182:185], v[240:243], v[64:67]
	v_mfma_f32_16x16x32_bf16 v[116:119], v[168:171], v[194:197], v[116:119]
	v_mfma_f32_16x16x32_bf16 v[112:115], v[186:189], v[194:197], v[112:115]
	v_mfma_f32_16x16x32_bf16 v[100:103], v[168:171], v[202:205], v[100:103]
	v_mfma_f32_16x16x32_bf16 v[96:99], v[186:189], v[202:205], v[96:99]
	s_setprio 2
	s_barrier
; #define PG8_STAGE(bufoff, gbase, voff) do { _Pragma("unroll") for (int _i = 0; _i < 2; ++_i) \
;         __builtin_amdgcn_global_load_lds((const unsigned*)((const char*)(gbase) + (voff)[_i]), (PG8_LAS unsigned*)(lds + (bufoff) + ldsw + _i * 8192), 16, 0, 0); } while (0)
; #define PG8_LDA(dst, b, h) do { _Pragma("unroll") for (int m = 0; m < 4; ++m) _Pragma("unroll") for (int k = 0; k < 2; ++k) dst[m][k] = *(const PG8_LAS bf16x8*)(lds + PG8_SA(b, h) + aoff + m * 2048 + k * 1024); } while (0)
; #define PG8_MMA(ai, bj, At, Bt) do { __builtin_amdgcn_s_setprio(1); _Pragma("unroll") for (int m = 0; m < 4; ++m) _Pragma("unroll") for (int n = 0; n < 2; ++n) _Pragma("unroll") for (int k = 0; k < 2; ++k) \
;         acc[ai][bj][m][n] = __builtin_amdgcn_mfma_f32_16x16x32_bf16(Bt[n][k], At[m][k], acc[ai][bj][m][n], 0, 0, 0); __builtin_amdgcn_s_setprio(0); } while (0)
; #define PG8_WAIT_V(n) asm volatile("s_waitcnt vmcnt(" #n ")" ::: "memory")
; #define PG8_WAIT_L(n) asm volatile("s_waitcnt lgkmcnt(" #n ")" ::: "memory")
; #define PG8_BAR __builtin_amdgcn_s_barrier()
; #define PG8_SCHED __builtin_amdgcn_sched_barrier(0)
; template <class Epi, class Sched, bool ALIGN_EPI = false, bool SP2 = false>
; __device__ __forceinline__ void gemm_phase(PG8_LAS unsigned char* lds, const Gemm g, const Sched& S, const Epi& E) {
;     ...
;             PG8_LDA(At, 1, 1); PG8_STAGE(PG8_SB(1, 0), b3, voffB); PG8_STAGE(PG8_SB(1, 1), b3 + hstep, voffB); PG8_STAGE(PG8_SA(1, 0), a3, voffA);
;             PG8_WAIT_V(8); PG8_WAIT_L(0); PG8_BAR; PG8_MMA(1, 0, At, B0); PG8_MMA(1, 1, At, B1); PG8_BAR; PG8_SCHED;
	v_mfma_f32_16x16x32_bf16 v[84:87], v[168:171], v[236:239], v[84:87]
	v_mfma_f32_16x16x32_bf16 v[80:83], v[186:189], v[236:239], v[80:83]
	v_mfma_f32_16x16x32_bf16 v[68:71], v[168:171], v[244:247], v[68:71]
	v_mfma_f32_16x16x32_bf16 v[64:67], v[186:189], v[244:247], v[64:67]
	s_setprio 0
	s_add_i32 s24, s39, s26
	s_mov_b32 m0, s24
	s_nop 0
	global_load_lds_dwordx4 v130, s[64:65]
	s_add_i32 m0, s24, 0x2000
	s_nop 0
	global_load_lds_dwordx4 v134, s[64:65]
	s_add_u32 s22, s22, 0x40080
	s_addc_u32 s23, s23, 0
	s_add_i32 s24, s45, s26
	s_mov_b32 m0, s24
	s_nop 0
	global_load_lds_dwordx4 v130, s[22:23]
	s_add_i32 m0, s24, 0x2000
	s_nop 0
	global_load_lds_dwordx4 v134, s[22:23]
	s_mov_b32 m0, s30
	s_nop 0
	global_load_lds_dwordx4 v128, s[68:69]
	s_mov_b32 m0, s31
	s_nop 0
	global_load_lds_dwordx4 v132, s[68:69]
	ds_read_b128 v[190:193], v154 offset:49152
	ds_read_b128 v[194:197], v154 offset:50176
	ds_read_b128 v[198:201], v154 offset:51200
	ds_read_b128 v[202:205], v154 offset:52224
	ds_read_b128 v[228:231], v154 offset:53248
	ds_read_b128 v[236:239], v154 offset:54272
	ds_read_b128 v[240:243], v154 offset:55296
	ds_read_b128 v[244:247], v154 offset:56320
	s_waitcnt vmcnt(8)
	s_waitcnt lgkmcnt(0)
	s_barrier
	s_setprio 1
	s_waitcnt lgkmcnt(0)
	v_mfma_f32_16x16x32_bf16 v[60:63], v[140:143], v[190:193], v[60:63]
	v_mfma_f32_16x16x32_bf16 v[56:59], v[156:159], v[190:193], v[56:59]
	v_mfma_f32_16x16x32_bf16 v[44:47], v[140:143], v[198:201], v[44:47]
	v_mfma_f32_16x16x32_bf16 v[40:43], v[156:159], v[198:201], v[40:43]
	v_mfma_f32_16x16x32_bf16 v[28:31], v[140:143], v[228:231], v[28:31]
	v_mfma_f32_16x16x32_bf16 v[24:27], v[156:159], v[228:231], v[24:27]
	v_mfma_f32_16x16x32_bf16 v[12:15], v[140:143], v[240:243], v[12:15]
	v_mfma_f32_16x16x32_bf16 v[8:11], v[156:159], v[240:243], v[8:11]
	v_mfma_f32_16x16x32_bf16 v[60:63], v[144:147], v[194:197], v[60:63]
	v_mfma_f32_16x16x32_bf16 v[56:59], v[160:163], v[194:197], v[56:59]
	v_mfma_f32_16x16x32_bf16 v[44:47], v[144:147], v[202:205], v[44:47]
	v_mfma_f32_16x16x32_bf16 v[40:43], v[160:163], v[202:205], v[40:43]
	v_mfma_f32_16x16x32_bf16 v[28:31], v[144:147], v[236:239], v[28:31]
	v_mfma_f32_16x16x32_bf16 v[24:27], v[160:163], v[236:239], v[24:27]
	v_mfma_f32_16x16x32_bf16 v[12:15], v[144:147], v[244:247], v[12:15]
	v_mfma_f32_16x16x32_bf16 v[8:11], v[160:163], v[244:247], v[8:11]
	s_setprio 0
	s_setprio 1
	v_mfma_f32_16x16x32_bf16 v[52:55], v[164:167], v[190:193], v[52:55]
	v_mfma_f32_16x16x32_bf16 v[48:51], v[182:185], v[190:193], v[48:51]
	v_mfma_f32_16x16x32_bf16 v[36:39], v[164:167], v[198:201], v[36:39]
	v_mfma_f32_16x16x32_bf16 v[32:35], v[182:185], v[198:201], v[32:35]
	v_mfma_f32_16x16x32_bf16 v[20:23], v[164:167], v[228:231], v[20:23]
	v_mfma_f32_16x16x32_bf16 v[16:19], v[182:185], v[228:231], v[16:19]
	v_mfma_f32_16x16x32_bf16 v[4:7], v[164:167], v[240:243], v[4:7]
	v_mfma_f32_16x16x32_bf16 v[0:3], v[182:185], v[240:243], v[0:3]
	v_mfma_f32_16x16x32_bf16 v[52:55], v[168:171], v[194:197], v[52:55]
	v_mfma_f32_16x16x32_bf16 v[48:51], v[186:189], v[194:197], v[48:51]
	v_mfma_f32_16x16x32_bf16 v[36:39], v[168:171], v[202:205], v[36:39]
	v_mfma_f32_16x16x32_bf16 v[32:35], v[186:189], v[202:205], v[32:35]
	s_setprio 2
	s_barrier
	v_mfma_f32_16x16x32_bf16 v[20:23], v[168:171], v[236:239], v[20:23]
	v_mfma_f32_16x16x32_bf16 v[16:19], v[186:189], v[236:239], v[16:19]
	v_mfma_f32_16x16x32_bf16 v[4:7], v[168:171], v[244:247], v[4:7]
	v_mfma_f32_16x16x32_bf16 v[0:3], v[186:189], v[244:247], v[0:3]
	s_setprio 0
	s_add_i32 s38, s38, 2
	s_add_u32 s20, s20, 0x100
	s_addc_u32 s21, s21, 0
	s_add_u32 s36, s36, 0x100
	s_addc_u32 s37, s37, 0
	s_cmp_gt_u32 s38, 13
	s_cbranch_scc0 .LBB0_274
	s_and_b64 vcc, exec, s[8:9]
	s_cbranch_vccz .LBB0_295
	s_barrier
	v_lshl_add_u32 v155, s4, 8, v150
	s_cmp_gt_i32 s18, 7
	s_mov_b64 s[4:5], -1
	s_cbranch_scc1 .LBB0_296
